# prep: gate/up and w_in weight-transpose items rewritten by hand: 32 W loads issued back to back, per-k gain applied after the LDS transpose (same f32 products)
# speedup vs baseline: 1.0105x; 1.0105x over previous
; #define LAS __attribute__((address_space(3)))
; __device__ __forceinline__ void tr_item(const float* W, int ldw, int K, int k0, int srccol0, bf16* WT, int dstrow0, const float* gain, float scale, LAS float* scr, int lane, const float* gain2 = nullptr) {
;     ...
;     for (int i = 0; i < 32; ++i) { const int kk = 2 * i + (lane >> 5); float gsc = gain ? gain[k0 + kk] * scale : scale; if (gain2) gsc *= gain2[k0 + kk]; scr[kk * 33 + (lane & 31)] = W[(size_t)(k0 + kk) * ldw + srccol0 + (lane & 31)] * gsc; }
; __device__ __forceinline__ void phase_prep(const Args& a, unsigned char* ws, LAS unsigned char* lds, int vcu, int G, int tid, int wid, int lane) {
;     LAS float* scr = (LAS float*)(lds + wid * 16384);
;     const int gw = vcu * 8 + wid, NGW = G * 8;
;     constexpr int I_GU = 16 * 176, I_D = 44 * 32, I_IN = 16 * 112, I_OUT = 16 * 32, I_L = 2 * I_GU + 2 * I_D + I_IN + I_OUT;
;     for (int it = gw; it < 2 * I_L; it += NGW) {
.LBB0_10:
	s_ashr_i32 s61, s60, 31
	s_add_u32 s6, s66, s60
	s_addc_u32 s7, s67, s61
	s_ashr_i32 s0, s0, 6
	s_lshl_b32 s1, s63, 3
	v_and_b32_e32 v66, 63, v1
	s_add_i32 s18, s1, s0
	s_lshl_b32 s64, s62, 3
	s_cmpk_gt_i32 s18, 0x53ff
	v_lshlrev_b32_e32 v68, 3, v66
	s_cbranch_scc1 .LBB0_228
	v_lshrrev_b32_e32 v2, 5, v66
	s_movk_i32 s3, 0x84
	v_mov_b32_e32 v3, 0x108
	v_mad_u32_u24 v6, v2, s3, v3
	v_mov_b32_e32 v3, 0x210
	v_mad_u32_u24 v18, v2, s3, v3
	v_mov_b32_e32 v3, 0x318
	v_mad_u32_u24 v10, v2, s3, v3
	v_mov_b32_e32 v3, 0x420
	v_mad_u32_u24 v21, v2, s3, v3
	v_mov_b32_e32 v3, 0x528
	v_mad_u32_u24 v11, v2, s3, v3
	v_mov_b32_e32 v3, 0x630
	v_mad_u32_u24 v24, v2, s3, v3
	v_mov_b32_e32 v3, 0x738
	v_mad_u32_u24 v12, v2, s3, v3
	v_mov_b32_e32 v3, 0x840
	v_mad_u32_u24 v27, v2, s3, v3
	v_mov_b32_e32 v3, 0x948
	v_mad_u32_u24 v13, v2, s3, v3
	v_mov_b32_e32 v3, 0xa50
	v_mad_u32_u24 v30, v2, s3, v3
	v_mov_b32_e32 v3, 0xb58
	v_mad_u32_u24 v14, v2, s3, v3
	v_mov_b32_e32 v3, 0xc60
	v_mad_u32_u24 v33, v2, s3, v3
	v_mov_b32_e32 v3, 0xd68
	v_mad_u32_u24 v15, v2, s3, v3
	v_mov_b32_e32 v3, 0xe70
	v_mad_u32_u24 v36, v2, s3, v3
	v_mov_b32_e32 v3, 0xf78
	v_mad_u32_u24 v56, v2, s3, v3
	v_mov_b32_e32 v3, 0x1080
	v_mad_u32_u24 v39, v2, s3, v3
	v_mov_b32_e32 v3, 0x1188
	v_mad_u32_u24 v57, v2, s3, v3
	v_mov_b32_e32 v3, 0x1290
	v_mad_u32_u24 v42, v2, s3, v3
	v_mov_b32_e32 v3, 0x1398
	s_load_dwordx4 s[8:11], s[78:79], 0x28
	s_add_i32 s1, s60, 0
	s_lshl_b32 s0, s0, 14
	v_mad_u32_u24 v58, v2, s3, v3
	v_mov_b32_e32 v3, 0x14a0
	s_add_i32 s2, s1, s0
	v_mad_u32_u24 v44, v2, s3, v3
	v_mov_b32_e32 v3, 0x15a8
	s_add_u32 s0, s6, 0x1000000
	v_mad_u32_u24 v59, v2, s3, v3
	v_mov_b32_e32 v3, 0x16b0
	s_load_dwordx4 s[12:15], s[78:79], 0x98
	s_load_dwordx2 s[22:23], s[78:79], 0x78
	s_load_dwordx2 s[24:25], s[78:79], 0x38
	s_addc_u32 s1, s7, 0
	v_mad_u32_u24 v45, v2, s3, v3
	v_mov_b32_e32 v3, 0x17b8
	v_lshrrev_b32_e32 v46, 3, v66
	v_and_b32_e32 v8, 56, v68
	v_and_b32_e32 v4, 31, v1
	v_mad_u32_u24 v60, v2, s3, v3
	v_mul_u32_u24_e32 v3, 0x84, v8
	v_lshlrev_b32_e32 v47, 2, v46
	s_waitcnt lgkmcnt(0)
	s_cmp_lg_u64 s[10:11], 0
	v_mov_b32_e32 v7, 0
	v_lshl_add_u32 v5, v4, 2, s2
	v_add3_u32 v47, s2, v3, v47
	v_mov_b32_e32 v3, 0x18c0
	s_cselect_b64 s[26:27], -1, 0
	s_cmp_lg_u64 s[14:15], 0
	s_mov_b32 s21, 0
	v_mul_u32_u24_e32 v9, 0x84, v2
	v_or_b32_e32 v16, 2, v2
	v_or_b32_e32 v17, 4, v2
	v_or_b32_e32 v19, 6, v2
	v_or_b32_e32 v20, 8, v2
	v_or_b32_e32 v22, 10, v2
	v_or_b32_e32 v23, 12, v2
	v_or_b32_e32 v25, 14, v2
	v_or_b32_e32 v26, 16, v2
	v_or_b32_e32 v28, 18, v2
	v_or_b32_e32 v29, 20, v2
	v_or_b32_e32 v31, 22, v2
	v_or_b32_e32 v32, 24, v2
	v_or_b32_e32 v34, 26, v2
	v_or_b32_e32 v35, 28, v2
	v_or_b32_e32 v37, 30, v2
	v_or_b32_e32 v38, 32, v2
	v_or_b32_e32 v40, 34, v2
	v_or_b32_e32 v41, 36, v2
	v_or_b32_e32 v43, 38, v2
	v_mad_u32_u24 v48, v2, s3, v3
	s_cselect_b64 s[28:29], -1, 0
	v_mov_b32_e32 v3, v7
	s_lshl_b32 s19, s18, 5
	s_lshl_b32 s33, s64, 5
	s_lshl_b32 s38, s18, 1
	s_lshl_b32 s39, s64, 1
	s_mov_b64 s[30:31], 0x2480000
	s_mov_b64 s[34:35], 0x1780000
	s_mov_b64 s[36:37], 0x1080000
	s_mov_b64 s[40:41], 0xb00000
	v_add_u32_e32 v49, v5, v6
	v_add_u32_e32 v50, v5, v10
	v_add_u32_e32 v51, v5, v11
	v_add_u32_e32 v52, v5, v12
	v_add_u32_e32 v53, v5, v13
	v_add_u32_e32 v54, v5, v14
	v_add_u32_e32 v55, v5, v15
	v_add_u32_e32 v56, v5, v56
	v_add_u32_e32 v57, v5, v57
	v_add_u32_e32 v58, v5, v58
	v_add_u32_e32 v59, v5, v59
	v_add_u32_e32 v60, v5, v60
	s_mov_b32 s44, s18
	v_or_b32_e32 v61, 40, v2
	v_or_b32_e32 v62, 42, v2
	v_or_b32_e32 v63, 44, v2
	v_or_b32_e32 v64, 46, v2
	v_or_b32_e32 v65, 48, v2
	v_or_b32_e32 v67, 50, v2
	v_or_b32_e32 v69, 52, v2
	v_or_b32_e32 v70, 54, v2
	v_or_b32_e32 v71, 56, v2
	v_or_b32_e32 v72, 58, v2
	v_or_b32_e32 v73, 60, v2
	v_or_b32_e32 v74, 62, v2
	v_or_b32_e32 v75, 8, v46
	v_or_b32_e32 v76, 16, v46
	v_or_b32_e32 v77, 24, v46
	v_mov_b32_e32 v78, 0x3db504f3
	s_branch .LBB0_14
.LBB0_13:
	s_add_i32 s44, s44, s64
	s_add_i32 s19, s19, s33
	s_add_i32 s38, s38, s39
	s_cmpk_gt_i32 s44, 0x53ff
	s_cbranch_scc1 .LBB0_228

; __device__ __forceinline__ void tr_item(const float* W, int ldw, int K, int k0, int srccol0, bf16* WT, int dstrow0, const float* gain, float scale, LAS float* scr, int lane, const float* gain2 = nullptr) {
;     ...
;     for (int i = 0; i < 32; ++i) { const int kk = 2 * i + (lane >> 5); float gsc = gain ? gain[k0 + kk] * scale : scale; if (gain2) gsc *= gain2[k0 + kk]; scr[kk * 33 + (lane & 31)] = W[(size_t)(k0 + kk) * ldw + srccol0 + (lane & 31)] * gsc; }
; __device__ __forceinline__ void phase_prep(const Args& a, unsigned char* ws, LAS unsigned char* lds, int vcu, int G, int tid, int wid, int lane) {
;     ...
;             tr_item(a.in[7] + (size_t)l * DM * NIN, NIN, DM, kb * 64, src, (bf16*)(wl + WO_IN), n0, a.in[6] + l * DM, type == 1 ? 0.08838834764831845f : 1.f, scr, lane);
.LBB0_27:
	s_mul_i32 s3, s4, 0xe00000
	s_mul_hi_i32 s2, s4, 0xe00000
	s_add_u32 s53, s24, s3
	s_addc_u32 s54, s25, s2
	s_lshl_b32 s2, s49, 6
	s_and_b32 s49, s2, 0xffc0
	s_lshl_b32 s2, s4, 10
	s_ashr_i32 s3, s2, 31
	s_lshl_b64 s[2:3], s[2:3], 2
	s_add_u32 s50, s10, s2
	s_addc_u32 s51, s11, s3
	s_and_b32 s2, s52, 0x70
	s_cmp_eq_u32 s2, 16
	s_cselect_b64 vcc, -1, 0
	s_lshl_b64 s[2:3], s[20:21], 2
	s_add_u32 s2, s53, s2
	s_addc_u32 s3, s54, s3
	s_mul_i32 s20, s49, 0x3800
	s_add_u32 s98, s2, s20
	s_addc_u32 s99, s3, 0
	s_lshl_b32 s20, s49, 2
	s_add_u32 s100, s50, s20
	s_addc_u32 s101, s51, 0
	s_lshl_b32 s2, s49, 1
	s_lshl_b32 s3, s5, 11
	s_add_i32 s2, s2, s3
	s_add_u32 s2, s46, s2
	s_addc_u32 s3, s45, 0
	s_add_u32 s2, s2, s36
	s_addc_u32 s3, s3, s37
	v_mul_u32_u24_e32 v118, 0x3800, v2
	v_lshlrev_b32_e32 v119, 2, v8
	v_lshl_add_u32 v118, v4, 2, v118
	s_nop 0
	global_load_dwordx4 v[152:155], v119, s[100:101]
	global_load_dwordx4 v[156:159], v119, s[100:101] offset:16
	global_load_dword v120, v118, s[98:99]
	s_add_u32 s98, s98, 0x7000
	s_addc_u32 s99, s99, 0
	global_load_dword v121, v118, s[98:99]
	s_add_u32 s98, s98, 0x7000
	s_addc_u32 s99, s99, 0
	global_load_dword v122, v118, s[98:99]
	s_add_u32 s98, s98, 0x7000
	s_addc_u32 s99, s99, 0
	global_load_dword v123, v118, s[98:99]
	s_add_u32 s98, s98, 0x7000
	s_addc_u32 s99, s99, 0
	global_load_dword v124, v118, s[98:99]
	s_add_u32 s98, s98, 0x7000
	s_addc_u32 s99, s99, 0
	global_load_dword v125, v118, s[98:99]
	s_add_u32 s98, s98, 0x7000
	s_addc_u32 s99, s99, 0
	global_load_dword v126, v118, s[98:99]
	s_add_u32 s98, s98, 0x7000
	s_addc_u32 s99, s99, 0
	global_load_dword v127, v118, s[98:99]
	s_add_u32 s98, s98, 0x7000
	s_addc_u32 s99, s99, 0
	global_load_dword v128, v118, s[98:99]
	s_add_u32 s98, s98, 0x7000
	s_addc_u32 s99, s99, 0
	global_load_dword v129, v118, s[98:99]
	s_add_u32 s98, s98, 0x7000
	s_addc_u32 s99, s99, 0
	global_load_dword v130, v118, s[98:99]
	s_add_u32 s98, s98, 0x7000
	s_addc_u32 s99, s99, 0
	global_load_dword v131, v118, s[98:99]
	s_add_u32 s98, s98, 0x7000
	s_addc_u32 s99, s99, 0
	global_load_dword v132, v118, s[98:99]
	s_add_u32 s98, s98, 0x7000
	s_addc_u32 s99, s99, 0
	global_load_dword v133, v118, s[98:99]
	s_add_u32 s98, s98, 0x7000
	s_addc_u32 s99, s99, 0
	global_load_dword v134, v118, s[98:99]
	s_add_u32 s98, s98, 0x7000
	s_addc_u32 s99, s99, 0
	global_load_dword v135, v118, s[98:99]
	s_add_u32 s98, s98, 0x7000
	s_addc_u32 s99, s99, 0
	global_load_dword v136, v118, s[98:99]
	s_add_u32 s98, s98, 0x7000
	s_addc_u32 s99, s99, 0
	global_load_dword v137, v118, s[98:99]
	s_add_u32 s98, s98, 0x7000
	s_addc_u32 s99, s99, 0
	global_load_dword v138, v118, s[98:99]
	s_add_u32 s98, s98, 0x7000
	s_addc_u32 s99, s99, 0
	global_load_dword v139, v118, s[98:99]
	s_add_u32 s98, s98, 0x7000
	s_addc_u32 s99, s99, 0
	global_load_dword v140, v118, s[98:99]
	s_add_u32 s98, s98, 0x7000
	s_addc_u32 s99, s99, 0
	global_load_dword v141, v118, s[98:99]
	s_add_u32 s98, s98, 0x7000
	s_addc_u32 s99, s99, 0
	global_load_dword v142, v118, s[98:99]
	s_add_u32 s98, s98, 0x7000
	s_addc_u32 s99, s99, 0
	global_load_dword v143, v118, s[98:99]
	s_add_u32 s98, s98, 0x7000
	s_addc_u32 s99, s99, 0
	global_load_dword v144, v118, s[98:99]
	s_add_u32 s98, s98, 0x7000
	s_addc_u32 s99, s99, 0
	global_load_dword v145, v118, s[98:99]
	s_add_u32 s98, s98, 0x7000
	s_addc_u32 s99, s99, 0
	global_load_dword v146, v118, s[98:99]
	s_add_u32 s98, s98, 0x7000
	s_addc_u32 s99, s99, 0
	global_load_dword v147, v118, s[98:99]
	s_add_u32 s98, s98, 0x7000
	s_addc_u32 s99, s99, 0
	global_load_dword v148, v118, s[98:99]
	s_add_u32 s98, s98, 0x7000
	s_addc_u32 s99, s99, 0
	global_load_dword v149, v118, s[98:99]
	s_add_u32 s98, s98, 0x7000
	s_addc_u32 s99, s99, 0
	global_load_dword v150, v118, s[98:99]
	s_add_u32 s98, s98, 0x7000
	s_addc_u32 s99, s99, 0
	global_load_dword v151, v118, s[98:99]
	v_cndmask_b32_e32 v184, 1.0, v78, vcc
	v_add_u32_e32 v119, v5, v9
	s_waitcnt vmcnt(28)
	ds_write_b32 v119, v120
	ds_write_b32 v119, v121 offset:264
	ds_write_b32 v119, v122 offset:528
	ds_write_b32 v119, v123 offset:792
	s_waitcnt vmcnt(24)
	ds_write_b32 v119, v124 offset:1056
	ds_write_b32 v119, v125 offset:1320
	ds_write_b32 v119, v126 offset:1584
	ds_write_b32 v119, v127 offset:1848
	s_waitcnt vmcnt(20)
	ds_write_b32 v119, v128 offset:2112
	ds_write_b32 v119, v129 offset:2376
	ds_write_b32 v119, v130 offset:2640
	ds_write_b32 v119, v131 offset:2904
	s_waitcnt vmcnt(16)
; #define LAS __attribute__((address_space(3)))
; #define LDS_WAIT() asm volatile("s_waitcnt lgkmcnt(0)" ::: "memory")
; __device__ __forceinline__ unsigned pkbf(float lo, float hi) { typedef __bf16 bf2_t __attribute__((ext_vector_type(2))); f32x2 v = {lo, hi}; bf2_t b = __builtin_convertvector(v, bf2_t); return __builtin_bit_cast(unsigned, b); }
; __device__ __forceinline__ void tr_item(const float* W, int ldw, int K, int k0, int srccol0, bf16* WT, int dstrow0, const float* gain, float scale, LAS float* scr, int lane, const float* gain2 = nullptr) {
;     ...
;     for (int i = 0; i < 32; ++i) { const int kk = 2 * i + (lane >> 5); float gsc = gain ? gain[k0 + kk] * scale : scale; if (gain2) gsc *= gain2[k0 + kk]; scr[kk * 33 + (lane & 31)] = W[(size_t)(k0 + kk) * ldw + srccol0 + (lane & 31)] * gsc; }
;     LDS_WAIT();
;     const int c = lane & 7;
; #pragma unroll
;     for (int j = 0; j < 4; ++j) { const int n = (lane >> 3) + 8 * j; const LAS float* s = scr + (8 * c) * 33 + n;
;         u32x4 o; o.x = pkbf(s[0 * 33], s[1 * 33]); o.y = pkbf(s[2 * 33], s[3 * 33]); o.z = pkbf(s[4 * 33], s[5 * 33]); o.w = pkbf(s[6 * 33], s[7 * 33]);
;         *(u32x4*)(WT + (size_t)(dstrow0 + n) * K + k0 + 8 * c) = o; }
;     LDS_WAIT();
	ds_write_b32 v119, v132 offset:3168
	ds_write_b32 v119, v133 offset:3432
	ds_write_b32 v119, v134 offset:3696
	ds_write_b32 v119, v135 offset:3960
	s_waitcnt vmcnt(12)
	ds_write_b32 v119, v136 offset:4224
	ds_write_b32 v119, v137 offset:4488
	ds_write_b32 v119, v138 offset:4752
	ds_write_b32 v119, v139 offset:5016
	s_waitcnt vmcnt(8)
	ds_write_b32 v119, v140 offset:5280
	ds_write_b32 v119, v141 offset:5544
	ds_write_b32 v119, v142 offset:5808
	ds_write_b32 v119, v143 offset:6072
	s_waitcnt vmcnt(4)
	ds_write_b32 v119, v144 offset:6336
	ds_write_b32 v119, v145 offset:6600
	ds_write_b32 v119, v146 offset:6864
	ds_write_b32 v119, v147 offset:7128
	s_waitcnt vmcnt(0)
	ds_write_b32 v119, v148 offset:7392
	ds_write_b32 v119, v149 offset:7656
	ds_write_b32 v119, v150 offset:7920
	ds_write_b32 v119, v151 offset:8184
	v_mul_f32_e32 v152, v184, v152
	v_mul_f32_e32 v153, v184, v153
	v_mul_f32_e32 v154, v184, v154
	v_mul_f32_e32 v155, v184, v155
	v_mul_f32_e32 v156, v184, v156
	v_mul_f32_e32 v157, v184, v157
	v_mul_f32_e32 v158, v184, v158
	v_mul_f32_e32 v159, v184, v159
	s_waitcnt lgkmcnt(0)
	ds_read2_b32 v[120:121], v47 offset1:8
	ds_read2_b32 v[122:123], v47 offset0:33 offset1:41
	ds_read2_b32 v[124:125], v47 offset0:66 offset1:74
	ds_read2_b32 v[126:127], v47 offset0:99 offset1:107
	ds_read2_b32 v[128:129], v47 offset0:132 offset1:140
	ds_read2_b32 v[130:131], v47 offset0:165 offset1:173
	ds_read2_b32 v[132:133], v47 offset0:198 offset1:206
	ds_read2_b32 v[134:135], v47 offset0:231 offset1:239
	ds_read2_b32 v[136:137], v47 offset0:16 offset1:24
	ds_read2_b32 v[138:139], v47 offset0:49 offset1:57
	ds_read2_b32 v[140:141], v47 offset0:82 offset1:90
	ds_read2_b32 v[142:143], v47 offset0:115 offset1:123
	ds_read2_b32 v[144:145], v47 offset0:148 offset1:156
	ds_read2_b32 v[146:147], v47 offset0:181 offset1:189
	ds_read2_b32 v[148:149], v47 offset0:214 offset1:222
	ds_read2_b32 v[150:151], v47 offset0:247 offset1:255
	v_lshlrev_b32_e32 v118, 11, v46
	v_lshl_add_u32 v118, v8, 1, v118
	v_add_u32_e32 v186, 0x4000, v118
	v_add_u32_e32 v187, 0x8000, v118
	v_add_u32_e32 v188, 0xc000, v118
	s_waitcnt lgkmcnt(15)
	v_pk_mul_f32 v[120:121], v[120:121], v[152:153] op_sel_hi:[1,0]
	s_waitcnt lgkmcnt(14)
	v_pk_mul_f32 v[122:123], v[122:123], v[152:153] op_sel:[0,1] op_sel_hi:[1,1]
	s_waitcnt lgkmcnt(13)
	v_pk_mul_f32 v[124:125], v[124:125], v[154:155] op_sel_hi:[1,0]
	s_waitcnt lgkmcnt(12)
	v_pk_mul_f32 v[126:127], v[126:127], v[154:155] op_sel:[0,1] op_sel_hi:[1,1]
	s_waitcnt lgkmcnt(11)
	v_pk_mul_f32 v[128:129], v[128:129], v[156:157] op_sel_hi:[1,0]
	s_waitcnt lgkmcnt(10)
	v_pk_mul_f32 v[130:131], v[130:131], v[156:157] op_sel:[0,1] op_sel_hi:[1,1]
	s_waitcnt lgkmcnt(9)
	v_pk_mul_f32 v[132:133], v[132:133], v[158:159] op_sel_hi:[1,0]
	s_waitcnt lgkmcnt(8)
	v_pk_mul_f32 v[134:135], v[134:135], v[158:159] op_sel:[0,1] op_sel_hi:[1,1]
	v_cvt_pk_bf16_f32 v168, v120, v122
	v_cvt_pk_bf16_f32 v169, v124, v126
	v_cvt_pk_bf16_f32 v170, v128, v130
	v_cvt_pk_bf16_f32 v171, v132, v134
	global_store_dwordx4 v118, v[168:171], s[2:3]
	v_cvt_pk_bf16_f32 v172, v121, v123
	v_cvt_pk_bf16_f32 v173, v125, v127
	v_cvt_pk_bf16_f32 v174, v129, v131
	v_cvt_pk_bf16_f32 v175, v133, v135
	global_store_dwordx4 v186, v[172:175], s[2:3]
	s_waitcnt lgkmcnt(7)
	v_pk_mul_f32 v[136:137], v[136:137], v[152:153] op_sel_hi:[1,0]
	s_waitcnt lgkmcnt(6)
	v_pk_mul_f32 v[138:139], v[138:139], v[152:153] op_sel:[0,1] op_sel_hi:[1,1]
	s_waitcnt lgkmcnt(5)
	v_pk_mul_f32 v[140:141], v[140:141], v[154:155] op_sel_hi:[1,0]
	s_waitcnt lgkmcnt(4)
	v_pk_mul_f32 v[142:143], v[142:143], v[154:155] op_sel:[0,1] op_sel_hi:[1,1]
	s_waitcnt lgkmcnt(3)
	v_pk_mul_f32 v[144:145], v[144:145], v[156:157] op_sel_hi:[1,0]
	s_waitcnt lgkmcnt(2)
	v_pk_mul_f32 v[146:147], v[146:147], v[156:157] op_sel:[0,1] op_sel_hi:[1,1]
	s_waitcnt lgkmcnt(1)
	v_pk_mul_f32 v[148:149], v[148:149], v[158:159] op_sel_hi:[1,0]
	s_waitcnt lgkmcnt(0)
	v_pk_mul_f32 v[150:151], v[150:151], v[158:159] op_sel:[0,1] op_sel_hi:[1,1]
	v_cvt_pk_bf16_f32 v176, v136, v138
	v_cvt_pk_bf16_f32 v177, v140, v142
	v_cvt_pk_bf16_f32 v178, v144, v146
	v_cvt_pk_bf16_f32 v179, v148, v150
	global_store_dwordx4 v187, v[176:179], s[2:3]
	v_cvt_pk_bf16_f32 v180, v137, v139
	v_cvt_pk_bf16_f32 v181, v141, v143
	v_cvt_pk_bf16_f32 v182, v145, v147
	v_cvt_pk_bf16_f32 v183, v149, v151
	global_store_dwordx4 v188, v[180:183], s[2:3]

; __device__ __forceinline__ void tr_item(const float* W, int ldw, int K, int k0, int srccol0, bf16* WT, int dstrow0, const float* gain, float scale, LAS float* scr, int lane, const float* gain2 = nullptr) {
;     ...
;     for (int i = 0; i < 32; ++i) { const int kk = 2 * i + (lane >> 5); float gsc = gain ? gain[k0 + kk] * scale : scale; if (gain2) gsc *= gain2[k0 + kk]; scr[kk * 33 + (lane & 31)] = W[(size_t)(k0 + kk) * ldw + srccol0 + (lane & 31)] * gsc; }
; __device__ __forceinline__ void phase_prep(const Args& a, unsigned char* ws, LAS unsigned char* lds, int vcu, int G, int tid, int wid, int lane) {
;     ...
;             const int kb = r / 176, nb = r % 176, n0 = nb * 32, pn = n0 >> 8, half = (n0 >> 7) & 1, j0 = n0 & 127;
;             const float* src = a.in[second ? (half ? 18 : 17) : (half ? 4 : 3)] + (size_t)l * DM * FF;
;             tr_item(src, FF, DM, kb * 64, pn * 128 + j0, (bf16*)(wl + (second ? WO_GU2 : WO_GU1)), n0, a.in[second ? 16 : 2] + l * DM, 1.f, scr, lane, (!second && l > 0) ? a.in[20] + (l - 1) * DM : nullptr);
.LBB0_80:
	s_andn2_b64 vcc, exec, s[2:3]
	s_cbranch_vccnz .LBB0_13
	s_and_b64 s[2:3], s[42:43], exec
	s_cselect_b32 s2, s47, s48
	s_sext_i32_i16 s3, s2
	s_mulk_i32 s3, 0xba3
	s_lshr_b32 s5, s3, 31
	s_ashr_i32 s3, s3, 19
	s_add_i32 s5, s3, s5
	s_and_b64 s[48:49], s[42:43], exec
	s_cselect_b32 s3, 3, 17
	s_lshl_b32 s50, s5, 6
	s_and_b64 s[48:49], s[42:43], exec
	s_cselect_b32 s20, 16, 0x80
	s_add_u32 s48, s78, s20
	s_addc_u32 s49, s79, 0
	s_load_dwordx2 s[48:49], s[48:49], 0x0
	s_mulk_i32 s5, 0xb0
	s_sub_i32 s2, s2, s5
	s_sext_i32_i16 s5, s2
	s_bfe_u32 s2, s2, 0x10002
	s_add_i32 s2, s2, s3
	s_lshl_b32 s2, s2, 3
	s_load_dwordx2 s[2:3], s[78:79], s2 offset:0x0
	s_lshl_b32 s52, s4, 12
	s_lshl_b32 s53, s50, 2
	s_add_i32 s52, s52, s53
	s_add_u32 s56, s14, s53
	s_addc_u32 s57, s15, 0
	s_cmpk_gt_i32 s44, 0x29ff
	s_cselect_b64 s[54:55], -1, 0
	s_and_b64 s[54:55], s[54:55], s[42:43]
	s_and_b64 s[58:59], s[54:55], s[28:29]
	s_lshl_b32 s20, s5, 5
	s_and_b32 s47, s20, 0x60
	s_lshl_b32 s51, s5, 4
	s_and_b32 s51, s51, 0xffffff80
	s_or_b32 s51, s51, s47
	s_mul_i32 s47, s50, 0xb00
	s_add_i32 s51, s51, s47
	s_lshl_b32 s51, s51, 2
	s_mul_hi_i32 s47, s4, 0xb00000
	s_mul_i32 s4, s4, 0xb00000
	s_add_u32 s4, s4, s51
	s_addc_u32 s47, s47, 0
	s_waitcnt lgkmcnt(0)
	s_add_u32 s98, s2, s4
	s_addc_u32 s99, s3, s47
	s_add_u32 s52, s48, s52
	s_addc_u32 s53, s49, 0
	s_and_b64 s[2:3], s[42:43], exec
	s_cselect_b32 s2, 0, 0x1980000
	s_add_u32 s4, s46, s2
	s_addc_u32 s5, s45, 0
	s_lshl_b32 s2, s50, 1
	s_lshl_b32 s3, s20, 11
	s_add_i32 s2, s2, s3
	s_add_u32 s2, s4, s2
	s_addc_u32 s3, s5, 0
	v_mul_u32_u24_e32 v118, 0x2c00, v2
	v_lshlrev_b32_e32 v119, 2, v8
	v_lshl_add_u32 v118, v4, 2, v118
	s_nop 0
	global_load_dwordx4 v[152:155], v119, s[52:53]
	global_load_dwordx4 v[156:159], v119, s[52:53] offset:16
	s_cmp_lg_u64 s[58:59], 0
	s_cbranch_scc0 .Lprep_gu_nog2a
	global_load_dwordx4 v[160:163], v119, s[56:57]
	global_load_dwordx4 v[164:167], v119, s[56:57] offset:16
.Lprep_gu_nog2a:
	global_load_dword v120, v118, s[98:99]
	s_add_u32 s98, s98, 0x5800
	s_addc_u32 s99, s99, 0
	global_load_dword v121, v118, s[98:99]
	s_add_u32 s98, s98, 0x5800
	s_addc_u32 s99, s99, 0
	global_load_dword v122, v118, s[98:99]
	s_add_u32 s98, s98, 0x5800
	s_addc_u32 s99, s99, 0
	global_load_dword v123, v118, s[98:99]
	s_add_u32 s98, s98, 0x5800
	s_addc_u32 s99, s99, 0
	global_load_dword v124, v118, s[98:99]
	s_add_u32 s98, s98, 0x5800
	s_addc_u32 s99, s99, 0
	global_load_dword v125, v118, s[98:99]
	s_add_u32 s98, s98, 0x5800
	s_addc_u32 s99, s99, 0
	global_load_dword v126, v118, s[98:99]
	s_add_u32 s98, s98, 0x5800
	s_addc_u32 s99, s99, 0
	global_load_dword v127, v118, s[98:99]
	s_add_u32 s98, s98, 0x5800
	s_addc_u32 s99, s99, 0
	global_load_dword v128, v118, s[98:99]
	s_add_u32 s98, s98, 0x5800
	s_addc_u32 s99, s99, 0
	global_load_dword v129, v118, s[98:99]
	s_add_u32 s98, s98, 0x5800
	s_addc_u32 s99, s99, 0
	global_load_dword v130, v118, s[98:99]
	s_add_u32 s98, s98, 0x5800
	s_addc_u32 s99, s99, 0
	global_load_dword v131, v118, s[98:99]
	s_add_u32 s98, s98, 0x5800
	s_addc_u32 s99, s99, 0
	global_load_dword v132, v118, s[98:99]
	s_add_u32 s98, s98, 0x5800
	s_addc_u32 s99, s99, 0
	global_load_dword v133, v118, s[98:99]
	s_add_u32 s98, s98, 0x5800
	s_addc_u32 s99, s99, 0
	global_load_dword v134, v118, s[98:99]
	s_add_u32 s98, s98, 0x5800
	s_addc_u32 s99, s99, 0
	global_load_dword v135, v118, s[98:99]
	s_add_u32 s98, s98, 0x5800
	s_addc_u32 s99, s99, 0
	global_load_dword v136, v118, s[98:99]
	s_add_u32 s98, s98, 0x5800
	s_addc_u32 s99, s99, 0
	global_load_dword v137, v118, s[98:99]
	s_add_u32 s98, s98, 0x5800
	s_addc_u32 s99, s99, 0
	global_load_dword v138, v118, s[98:99]
	s_add_u32 s98, s98, 0x5800
	s_addc_u32 s99, s99, 0
	global_load_dword v139, v118, s[98:99]
	s_add_u32 s98, s98, 0x5800
	s_addc_u32 s99, s99, 0
	global_load_dword v140, v118, s[98:99]
	s_add_u32 s98, s98, 0x5800
	s_addc_u32 s99, s99, 0
	global_load_dword v141, v118, s[98:99]
	s_add_u32 s98, s98, 0x5800
	s_addc_u32 s99, s99, 0
	global_load_dword v142, v118, s[98:99]
	s_add_u32 s98, s98, 0x5800
	s_addc_u32 s99, s99, 0
	global_load_dword v143, v118, s[98:99]
	s_add_u32 s98, s98, 0x5800
	s_addc_u32 s99, s99, 0
	global_load_dword v144, v118, s[98:99]
	s_add_u32 s98, s98, 0x5800
	s_addc_u32 s99, s99, 0
	global_load_dword v145, v118, s[98:99]
	s_add_u32 s98, s98, 0x5800
	s_addc_u32 s99, s99, 0
	global_load_dword v146, v118, s[98:99]
	s_add_u32 s98, s98, 0x5800
	s_addc_u32 s99, s99, 0
	global_load_dword v147, v118, s[98:99]
	s_add_u32 s98, s98, 0x5800
	s_addc_u32 s99, s99, 0
	global_load_dword v148, v118, s[98:99]
	s_add_u32 s98, s98, 0x5800
	s_addc_u32 s99, s99, 0
	global_load_dword v149, v118, s[98:99]
	s_add_u32 s98, s98, 0x5800
	s_addc_u32 s99, s99, 0
	global_load_dword v150, v118, s[98:99]
	s_add_u32 s98, s98, 0x5800
	s_addc_u32 s99, s99, 0
	global_load_dword v151, v118, s[98:99]
	v_add_u32_e32 v119, v5, v9
	s_waitcnt vmcnt(28)
	ds_write_b32 v119, v120
	ds_write_b32 v119, v121 offset:264
	ds_write_b32 v119, v122 offset:528
	ds_write_b32 v119, v123 offset:792
	s_waitcnt vmcnt(24)
	ds_write_b32 v119, v124 offset:1056
	ds_write_b32 v119, v125 offset:1320
	ds_write_b32 v119, v126 offset:1584
	ds_write_b32 v119, v127 offset:1848
	s_waitcnt vmcnt(20)
	ds_write_b32 v119, v128 offset:2112
	ds_write_b32 v119, v129 offset:2376
	ds_write_b32 v119, v130 offset:2640
	ds_write_b32 v119, v131 offset:2904
	s_waitcnt vmcnt(16)
	ds_write_b32 v119, v132 offset:3168
	ds_write_b32 v119, v133 offset:3432
	ds_write_b32 v119, v134 offset:3696
	ds_write_b32 v119, v135 offset:3960
	s_waitcnt vmcnt(12)
	ds_write_b32 v119, v136 offset:4224
	ds_write_b32 v119, v137 offset:4488
	ds_write_b32 v119, v138 offset:4752
	ds_write_b32 v119, v139 offset:5016
	s_waitcnt vmcnt(8)
	ds_write_b32 v119, v140 offset:5280
	ds_write_b32 v119, v141 offset:5544
	ds_write_b32 v119, v142 offset:5808
	ds_write_b32 v119, v143 offset:6072
	s_waitcnt vmcnt(4)
	ds_write_b32 v119, v144 offset:6336
	ds_write_b32 v119, v145 offset:6600
	ds_write_b32 v119, v146 offset:6864
	ds_write_b32 v119, v147 offset:7128
	s_waitcnt vmcnt(0)
	ds_write_b32 v119, v148 offset:7392
	ds_write_b32 v119, v149 offset:7656
	ds_write_b32 v119, v150 offset:7920
	ds_write_b32 v119, v151 offset:8184
	s_cmp_lg_u64 s[58:59], 0
	s_cbranch_scc0 .Lprep_gu_nog2b
	v_pk_mul_f32 v[152:153], v[152:153], v[160:161]
	v_pk_mul_f32 v[154:155], v[154:155], v[162:163]
	v_pk_mul_f32 v[156:157], v[156:157], v[164:165]
	v_pk_mul_f32 v[158:159], v[158:159], v[166:167]
; #define LAS __attribute__((address_space(3)))
; #define LDS_WAIT() asm volatile("s_waitcnt lgkmcnt(0)" ::: "memory")
; __device__ __forceinline__ unsigned pkbf(float lo, float hi) { typedef __bf16 bf2_t __attribute__((ext_vector_type(2))); f32x2 v = {lo, hi}; bf2_t b = __builtin_convertvector(v, bf2_t); return __builtin_bit_cast(unsigned, b); }
; __device__ __forceinline__ void tr_item(const float* W, int ldw, int K, int k0, int srccol0, bf16* WT, int dstrow0, const float* gain, float scale, LAS float* scr, int lane, const float* gain2 = nullptr) {
;     ...
;     for (int i = 0; i < 32; ++i) { const int kk = 2 * i + (lane >> 5); float gsc = gain ? gain[k0 + kk] * scale : scale; if (gain2) gsc *= gain2[k0 + kk]; scr[kk * 33 + (lane & 31)] = W[(size_t)(k0 + kk) * ldw + srccol0 + (lane & 31)] * gsc; }
;     LDS_WAIT();
;     const int c = lane & 7;
; #pragma unroll
;     for (int j = 0; j < 4; ++j) { const int n = (lane >> 3) + 8 * j; const LAS float* s = scr + (8 * c) * 33 + n;
;         u32x4 o; o.x = pkbf(s[0 * 33], s[1 * 33]); o.y = pkbf(s[2 * 33], s[3 * 33]); o.z = pkbf(s[4 * 33], s[5 * 33]); o.w = pkbf(s[6 * 33], s[7 * 33]);
;         *(u32x4*)(WT + (size_t)(dstrow0 + n) * K + k0 + 8 * c) = o; }
;     LDS_WAIT();
.Lprep_gu_nog2b:
	s_waitcnt lgkmcnt(0)
	ds_read2_b32 v[120:121], v47 offset1:8
	ds_read2_b32 v[122:123], v47 offset0:33 offset1:41
	ds_read2_b32 v[124:125], v47 offset0:66 offset1:74
	ds_read2_b32 v[126:127], v47 offset0:99 offset1:107
	ds_read2_b32 v[128:129], v47 offset0:132 offset1:140
	ds_read2_b32 v[130:131], v47 offset0:165 offset1:173
	ds_read2_b32 v[132:133], v47 offset0:198 offset1:206
	ds_read2_b32 v[134:135], v47 offset0:231 offset1:239
	ds_read2_b32 v[136:137], v47 offset0:16 offset1:24
	ds_read2_b32 v[138:139], v47 offset0:49 offset1:57
	ds_read2_b32 v[140:141], v47 offset0:82 offset1:90
	ds_read2_b32 v[142:143], v47 offset0:115 offset1:123
	ds_read2_b32 v[144:145], v47 offset0:148 offset1:156
	ds_read2_b32 v[146:147], v47 offset0:181 offset1:189
	ds_read2_b32 v[148:149], v47 offset0:214 offset1:222
	ds_read2_b32 v[150:151], v47 offset0:247 offset1:255
	v_lshlrev_b32_e32 v118, 11, v46
	v_lshl_add_u32 v118, v8, 1, v118
	v_add_u32_e32 v186, 0x4000, v118
	v_add_u32_e32 v187, 0x8000, v118
	v_add_u32_e32 v188, 0xc000, v118
	s_waitcnt lgkmcnt(15)
	v_pk_mul_f32 v[120:121], v[120:121], v[152:153] op_sel_hi:[1,0]
	s_waitcnt lgkmcnt(14)
	v_pk_mul_f32 v[122:123], v[122:123], v[152:153] op_sel:[0,1] op_sel_hi:[1,1]
	s_waitcnt lgkmcnt(13)
	v_pk_mul_f32 v[124:125], v[124:125], v[154:155] op_sel_hi:[1,0]
	s_waitcnt lgkmcnt(12)
	v_pk_mul_f32 v[126:127], v[126:127], v[154:155] op_sel:[0,1] op_sel_hi:[1,1]
	s_waitcnt lgkmcnt(11)
	v_pk_mul_f32 v[128:129], v[128:129], v[156:157] op_sel_hi:[1,0]
	s_waitcnt lgkmcnt(10)
	v_pk_mul_f32 v[130:131], v[130:131], v[156:157] op_sel:[0,1] op_sel_hi:[1,1]
	s_waitcnt lgkmcnt(9)
	v_pk_mul_f32 v[132:133], v[132:133], v[158:159] op_sel_hi:[1,0]
	s_waitcnt lgkmcnt(8)
	v_pk_mul_f32 v[134:135], v[134:135], v[158:159] op_sel:[0,1] op_sel_hi:[1,1]
	v_cvt_pk_bf16_f32 v168, v120, v122
	v_cvt_pk_bf16_f32 v169, v124, v126
	v_cvt_pk_bf16_f32 v170, v128, v130
	v_cvt_pk_bf16_f32 v171, v132, v134
	global_store_dwordx4 v118, v[168:171], s[2:3]
	v_cvt_pk_bf16_f32 v172, v121, v123
	v_cvt_pk_bf16_f32 v173, v125, v127
	v_cvt_pk_bf16_f32 v174, v129, v131
	v_cvt_pk_bf16_f32 v175, v133, v135
	global_store_dwordx4 v186, v[172:175], s[2:3]
	s_waitcnt lgkmcnt(7)
	v_pk_mul_f32 v[136:137], v[136:137], v[152:153] op_sel_hi:[1,0]
	s_waitcnt lgkmcnt(6)
	v_pk_mul_f32 v[138:139], v[138:139], v[152:153] op_sel:[0,1] op_sel_hi:[1,1]
	s_waitcnt lgkmcnt(5)
	v_pk_mul_f32 v[140:141], v[140:141], v[154:155] op_sel_hi:[1,0]
	s_waitcnt lgkmcnt(4)
	v_pk_mul_f32 v[142:143], v[142:143], v[154:155] op_sel:[0,1] op_sel_hi:[1,1]
	s_waitcnt lgkmcnt(3)
	v_pk_mul_f32 v[144:145], v[144:145], v[156:157] op_sel_hi:[1,0]
	s_waitcnt lgkmcnt(2)
	v_pk_mul_f32 v[146:147], v[146:147], v[156:157] op_sel:[0,1] op_sel_hi:[1,1]
	s_waitcnt lgkmcnt(1)
	v_pk_mul_f32 v[148:149], v[148:149], v[158:159] op_sel_hi:[1,0]
	s_waitcnt lgkmcnt(0)
	v_pk_mul_f32 v[150:151], v[150:151], v[158:159] op_sel:[0,1] op_sel_hi:[1,1]
	v_cvt_pk_bf16_f32 v176, v136, v138
	v_cvt_pk_bf16_f32 v177, v140, v142
	v_cvt_pk_bf16_f32 v178, v144, v146
	v_cvt_pk_bf16_f32 v179, v148, v150
	global_store_dwordx4 v187, v[176:179], s[2:3]
	v_cvt_pk_bf16_f32 v180, v137, v139
	v_cvt_pk_bf16_f32 v181, v141, v143
	v_cvt_pk_bf16_f32 v182, v145, v147
	v_cvt_pk_bf16_f32 v183, v149, v151
	global_store_dwordx4 v188, v[180:183], s[2:3]
	s_branch .LBB0_13
